# v68 + P6 row-statistics exchange at L2 scope (plain stores, sc0 loads) when the row panel's 8 workgroups are verified same-XCD; counter/polls stay agent scope
# baseline (speedup 1.0000x reference)
;     __device__ __forceinline__ void fused(f32x4 (&acc)[2][2][4][2], const Unit& u, int wr, int wc, int fr, int fq, PG8_LAS unsigned char* lds, int wid, int lane) const {
;     ...
; #pragma unroll
;         for (int ai = 0; ai < 2; ++ai)
; #pragma unroll
;             for (int m = 0; m < 4; ++m) { float q = 0.f;
; #pragma unroll
;                 for (int bj = 0; bj < 2; ++bj)
; #pragma unroll
;                     for (int n = 0; n < 2; ++n) { const f32x4 v = acc[ai][bj][m][n]; q += (v[0] * v[0] + v[1] * v[1]) + (v[2] * v[2] + v[3] * v[3]); }
;                 q += __shfl_xor(q, 16); q += __shfl_xor(q, 32);
;                 if (fq == 0) P[(ai * HALF + wr * 64 + m * 16 + fr) * 4 + wc] = q;
;                 }
;         asm volatile("s_waitcnt lgkmcnt(0)" ::: "memory"); __builtin_amdgcn_s_barrier(); asm volatile("" ::: "memory");
.LBB0_1044:
	s_lshl_b32 s53, s8, 5
	s_add_i32 s53, s53, 0x51000
	v_and_b32_e32 v200, 7, v254
	v_lshl_add_u32 v200, v200, 2, s53
	global_load_dword v200, v200, s[26:27] sc1
	v_mul_f32_e32 v133, v127, v127
	v_mul_f32_e32 v134, v129, v129
	v_fmac_f32_e32 v133, v126, v126
	v_fmac_f32_e32 v134, v128, v128
	v_add_f32_e32 v133, v133, v134
	v_mul_f32_e32 v134, v119, v119
	v_mul_f32_e32 v135, v121, v121
	v_fmac_f32_e32 v134, v118, v118
	v_fmac_f32_e32 v135, v120, v120
	v_add_f32_e32 v134, v134, v135
	v_mbcnt_lo_u32_b32 v130, -1, 0
	v_add_f32_e32 v133, v134, v133
	v_mul_f32_e32 v134, v111, v111
	v_mul_f32_e32 v135, v113, v113
	v_mbcnt_hi_u32_b32 v131, -1, v130
	v_fmac_f32_e32 v134, v110, v110
	v_fmac_f32_e32 v135, v112, v112
	v_and_b32_e32 v132, 64, v131
	v_add_f32_e32 v134, v134, v135
	v_xor_b32_e32 v130, 16, v131
	v_add_u32_e32 v132, 64, v132
	v_add_f32_e32 v133, v134, v133
	v_mul_f32_e32 v134, v107, v107
	v_mul_f32_e32 v135, v109, v109
	v_cmp_lt_i32_e32 vcc, v130, v132
	v_fmac_f32_e32 v134, v106, v106
	v_fmac_f32_e32 v135, v108, v108
	v_cndmask_b32_e32 v130, v131, v130, vcc
	v_add_f32_e32 v134, v134, v135
	v_lshlrev_b32_e32 v130, 2, v130
	v_add_f32_e32 v133, v134, v133
	ds_bpermute_b32 v134, v130, v133
	v_xor_b32_e32 v135, 32, v131
	v_cmp_lt_i32_e32 vcc, v135, v132
	s_lshl_b32 s0, s42, 2
	s_add_i32 s0, s0, 0
	v_cndmask_b32_e32 v131, v131, v135, vcc
	v_lshlrev_b32_e32 v131, 2, v131
	s_waitcnt lgkmcnt(0)
	v_add_f32_e32 v132, v133, v134
	ds_bpermute_b32 v133, v131, v132
	v_cmp_gt_u32_e32 vcc, 16, v254
	s_barrier
	s_and_saveexec_b64 s[2:3], vcc
	s_cbranch_execz .LBB0_1046
	s_lshl_b32 s1, s35, 10
	s_add_i32 s1, s0, s1
	s_waitcnt lgkmcnt(0)
	v_add_f32_e32 v132, v132, v133
	v_lshl_add_u32 v133, v154, 4, s1
	ds_write_b32 v133, v132

;     __device__ __forceinline__ void fused(f32x4 (&acc)[2][2][4][2], const Unit& u, int wr, int wc, int fr, int fq, PG8_LAS unsigned char* lds, int wid, int lane) const {
;     ...
;         const int row = wid * 32 + (lane & 31);
;         if (lane < 32) { const float t = (P[row * 4 + 0] + P[row * 4 + 1]) + (P[row * 4 + 2] + P[row * 4 + 3]);
;             __hip_atomic_store(xbuf + (size_t)(u.pm * BM + row) * 8 + u.pn, __float_as_uint(t), __ATOMIC_RELAXED, __HIP_MEMORY_SCOPE_AGENT); }
.LBB0_1060:
	s_or_b64 exec, exec, s[2:3]
	s_waitcnt lgkmcnt(0)
	s_barrier
	v_and_b32_e32 v130, 31, v0
	s_add_u32 s10, s26, 0x80000
	v_lshl_or_b32 v134, s13, 5, v130
	s_addc_u32 s11, s27, 0
	v_cmp_gt_u32_e64 s[2:3], 32, v254
	v_lshl_add_u32 v130, s8, 8, v134
	s_and_saveexec_b64 s[4:5], s[2:3]
	s_cbranch_execz .LBB0_1062
	s_waitcnt lgkmcnt(0)
	v_lshl_add_u32 v131, v134, 4, 0
	ds_read_b128 v[136:139], v131
	v_ashrrev_i32_e32 v131, 31, v130
	v_lshlrev_b64 v[132:133], 5, v[130:131]
	v_lshl_add_u64 v[132:133], s[10:11], 0, v[132:133]
	s_ashr_i32 s13, s12, 31
	s_waitcnt lgkmcnt(0)
	v_mov_b32_e32 v140, v137
	v_mov_b32_e32 v141, v138
	v_mov_b32_e32 v137, v139
	v_pk_add_f32 v[136:137], v[140:141], v[136:137]
	v_lshl_add_u64 v[132:133], s[12:13], 2, v[132:133]
	v_pk_add_f32 v[136:137], v[136:137], v[136:137] op_sel:[0,1] op_sel_hi:[1,0]
	s_waitcnt vmcnt(0)
	v_readlane_b32 s53, v200, 0
	s_nop 1
	v_cmp_ne_u32_e64 s[56:57], s53, v200
	s_and_b32 s54, s56, 0xff
	s_cmp_eq_u32 s54, 0
	s_cselect_b32 s54, 1, 0
	s_cmp_lg_u32 s53, 0
	s_cselect_b32 s54, s54, 0
	s_cmp_eq_u32 s54, 1
	s_cbranch_scc1 .Lx6_st_l2
	global_store_dword v[132:133], v136, off sc1
	s_branch .Lx6_st_j
.Lx6_st_l2:
	global_store_dword v[132:133], v136, off
.Lx6_st_j:
.LBB0_1062:
	s_or_b64 exec, exec, s[4:5]
	s_waitcnt vmcnt(0)
	s_add_u32 s0, s26, 0x20000
	s_addc_u32 s1, s27, 0
	v_cmp_ne_u32_e64 s[6:7], 0, v254
	v_cmp_eq_u32_e64 s[4:5], 0, v254
	s_and_saveexec_b64 s[14:15], s[4:5]
	s_cbranch_execz .LBB0_1065
	s_mov_b64 s[16:17], exec
	s_waitcnt lgkmcnt(0)
	v_mbcnt_lo_u32_b32 v131, s16, 0
	v_mbcnt_hi_u32_b32 v131, s17, v131
	v_cmp_eq_u32_e32 vcc, 0, v131
	s_and_b64 s[18:19], exec, vcc
	s_mov_b64 exec, s[18:19]
	s_cbranch_execz .LBB0_1065
	s_lshl_b32 s18, s8, 6
	s_ashr_i32 s19, s18, 31
	s_lshl_b64 s[18:19], s[18:19], 2
	s_add_u32 s18, s0, s18
	s_addc_u32 s19, s1, s19
	s_bcnt1_i32_b64 s9, s[16:17]
	v_mov_b32_e32 v131, 0
	v_mov_b32_e32 v132, s9
	global_atomic_add v131, v132, s[18:19]

;     __device__ __forceinline__ void fused(f32x4 (&acc)[2][2][4][2], const Unit& u, int wr, int wc, int fr, int fq, PG8_LAS unsigned char* lds, int wid, int lane) const {
;     ...
;         if (lane < 32) { const unsigned* slot = xbuf + (size_t)(u.pm * BM + row) * 8; float t = 0.f;
; #pragma unroll
;             for (int k = 0; k < 8; ++k) t += __uint_as_float(__hip_atomic_load(slot + k, __ATOMIC_RELAXED, __HIP_MEMORY_SCOPE_AGENT));
;             S[row] = rsqrtf(t * (1.f / DM) + EPS); }
.LBB0_1083:
	s_waitcnt vmcnt(0) lgkmcnt(0)
	s_barrier
	s_waitcnt lgkmcnt(0)
	v_mov_b32_e32 v131, 0
	ds_read_b32 v155, v131 offset:5120
	s_and_saveexec_b64 s[4:5], s[2:3]
	s_cbranch_execz .LBB0_1085
	v_ashrrev_i32_e32 v131, 31, v130
	v_lshlrev_b64 v[130:131], 5, v[130:131]
	v_lshl_add_u64 v[130:131], s[10:11], 0, v[130:131]
	s_cmp_eq_u32 s54, 1
	s_cbranch_scc1 .Lx6_ld_l2
	global_load_dword v132, v[130:131], off sc1
	global_load_dword v133, v[130:131], off offset:4 sc1
	global_load_dword v135, v[130:131], off offset:8 sc1
	global_load_dword v136, v[130:131], off offset:12 sc1
	global_load_dword v137, v[130:131], off offset:16 sc1
	global_load_dword v138, v[130:131], off offset:20 sc1
	global_load_dword v139, v[130:131], off offset:24 sc1
	s_nop 0
	global_load_dword v130, v[130:131], off offset:28 sc1
	s_branch .Lx6_ld_j
.Lx6_ld_l2:
	global_load_dword v132, v[130:131], off sc0
	global_load_dword v133, v[130:131], off offset:4 sc0
	global_load_dword v135, v[130:131], off offset:8 sc0
	global_load_dword v136, v[130:131], off offset:12 sc0
	global_load_dword v137, v[130:131], off offset:16 sc0
	global_load_dword v138, v[130:131], off offset:20 sc0
	global_load_dword v139, v[130:131], off offset:24 sc0
	s_nop 0
	global_load_dword v130, v[130:131], off offset:28 sc0
.Lx6_ld_j:
	v_mov_b32_e32 v131, 0x358637bd
	s_mov_b32 s0, 0x800000
	s_waitcnt vmcnt(0)
	v_add_f32_e32 v132, 0, v132
	v_add_f32_e32 v132, v132, v133
	v_add_f32_e32 v132, v132, v135
	v_add_f32_e32 v132, v132, v136
	v_add_f32_e32 v132, v132, v137
	v_add_f32_e32 v132, v132, v138
	v_add_f32_e32 v132, v132, v139
	v_add_f32_e32 v130, v132, v130
	v_fmac_f32_e32 v131, 0x3a000000, v130
	v_mul_f32_e32 v130, 0x4b800000, v131
	v_cmp_gt_f32_e32 vcc, s0, v131
	s_nop 1
	v_cndmask_b32_e32 v130, v131, v130, vcc
	v_rsq_f32_e32 v130, v130
	s_nop 0
	v_mul_f32_e32 v131, 0x45800000, v130
	v_cndmask_b32_e32 v130, v130, v131, vcc
	v_lshl_add_u32 v131, v134, 2, 0
	ds_write_b32 v131, v130 offset:4096
